# v26 plus MLA loop-bottom inline vmcnt drain folded into the pre-barrier wait
# speedup vs baseline: 1.0051x; 1.0008x over previous
.LBB0_543:
	s_add_i32 s30, s30, 2
	s_mov_b64 s[10:11], 0x4000
	s_addk_i32 s53, 0xff80
	s_addk_i32 s24, 0x80
	v_lshl_add_u64 v[188:189], v[188:189], 0, s[10:11]
	v_lshl_add_u64 v[190:191], v[190:191], 0, s[84:85]
	v_lshl_add_u64 v[192:193], v[192:193], 0, s[84:85]
	v_lshl_add_u64 v[194:195], v[194:195], 0, s[84:85]
	s_cmp_lt_u32 s30, s23
	v_lshl_add_u64 v[196:197], v[196:197], 0, s[84:85]
	s_waitcnt vmcnt(0) lgkmcnt(0)
	s_barrier
	s_cbranch_scc0 .LBB0_568
